# combined: v30 (diff L0 full softmax migration) + MLA L0 triple-buffer/DMA two tiles ahead with address block in the first score chain + GEMM static priority for waves 4-7 + 64-byte loop-head alignment
# speedup vs baseline: 1.0007x; 1.0007x over previous
.LBB0_891:
	s_lshr_b32 s16, s19, 6
	s_and_b64 s[12:13], s[12:13], exec
	s_cselect_b32 s12, s19, s16
	s_and_b32 s17, s12, 7
	s_mul_i32 s12, s9, 0xc00
	s_mul_hi_u32 s13, s8, 0xc00
	s_add_i32 s13, s13, s12
	s_mul_i32 s12, s8, 0xc00
	v_readlane_b32 s20, v242, 21
	v_readlane_b32 s21, v242, 22
	s_add_u32 s12, s20, s12
	s_addc_u32 s13, s21, s13
	s_mul_i32 s16, s17, 0x180
	s_add_u32 s28, s12, s16
	s_addc_u32 s29, s13, 0
	s_mul_i32 s12, s1, 0xc00
	s_mul_hi_u32 s13, s0, 0xc00
	s_add_i32 s13, s13, s12
	s_mul_i32 s12, s0, 0xc00
	s_add_u32 s12, s27, s12
	s_addc_u32 s13, s30, s13
	s_add_u32 s12, s12, s16
	s_mul_i32 s20, s15, 0x3000000
	s_mul_hi_u32 s21, s14, 0x3000000
	s_addc_u32 s13, s13, 0
	s_add_i32 s21, s21, s20
	s_mul_i32 s20, s14, 0x3000000
	s_add_u32 s20, s27, s20
	s_addc_u32 s21, s30, s21
	s_add_u32 s22, s20, s16
	s_addc_u32 s23, s21, 0
	s_lshl_b64 s[0:1], s[0:1], 12
	s_add_u32 s0, s31, s0
	s_addc_u32 s1, s34, s1
	s_lshl_b32 s16, s17, 9
	s_add_u32 s0, s0, s16
	s_addc_u32 s1, s1, 0
	s_add_u32 s24, s0, 0x100
	s_addc_u32 s25, s1, 0
	s_lshl_b64 s[14:15], s[14:15], 26
	s_add_u32 s14, s31, s14
	s_addc_u32 s15, s34, s15
	s_add_u32 s14, s14, s16
	s_addc_u32 s15, s15, 0
	s_add_u32 s33, s14, 0x100
	v_readfirstlane_b32 s68, v0
	s_addc_u32 s35, s15, 0
	s_lshr_b32 s20, s68, 6
	s_lshl_b32 s16, s20, 5
	v_or_b32_e32 v4, s16, v1
	v_mov_b64_e32 v[2:3], s[28:29]
	s_movk_i32 s14, 0xc00
	v_mad_u64_u32 v[2:3], s[14:15], v4, s14, v[2:3]
	s_andn2_b32 s68, s68, 63
	v_lshl_add_u64 v[2:3], v[2:3], 0, v[148:149]
	global_load_dwordx4 v[142:145], v[2:3], off
	global_load_dwordx4 v[138:141], v[2:3], off offset:32
	global_load_dwordx4 v[134:137], v[2:3], off offset:64
	global_load_dwordx4 v[130:133], v[2:3], off offset:96
	global_load_dwordx4 v[126:129], v[2:3], off offset:128
	global_load_dwordx4 v[122:125], v[2:3], off offset:160
	global_load_dwordx4 v[118:121], v[2:3], off offset:192
	global_load_dwordx4 v[114:117], v[2:3], off offset:224
	global_load_dwordx4 v[110:113], v[2:3], off offset:256
	global_load_dwordx4 v[106:109], v[2:3], off offset:288
	global_load_dwordx4 v[102:105], v[2:3], off offset:320
	global_load_dwordx4 v[98:101], v[2:3], off offset:352
	v_or_b32_e32 v2, s68, v166
	v_mul_hi_i32 v3, v2, s11
	v_lshrrev_b32_e32 v4, 31, v3
	v_ashrrev_i32_e32 v3, 2, v3
	v_add_u32_e32 v3, v3, v4
	v_mul_lo_u32 v4, v3, 24
	v_sub_u32_e32 v4, v2, v4
	v_mul_lo_u32 v5, v3, s18
	v_lshrrev_b32_e32 v3, 1, v3
	v_bitop3_b32 v3, v3, v4, 7 bitop3:0x6c
	v_lshl_add_u32 v160, v3, 3, v5
	v_add_u32_e32 v3, 0x200, v2
	v_mul_hi_i32 v4, v3, s11
	v_lshrrev_b32_e32 v5, 31, v4
	v_ashrrev_i32_e32 v4, 2, v4
	v_add_u32_e32 v4, v4, v5
	v_mul_lo_u32 v5, v4, 24
	v_sub_u32_e32 v3, v3, v5
	v_mul_lo_u32 v5, v4, s18
	v_lshrrev_b32_e32 v4, 1, v4
	v_bitop3_b32 v3, v4, v3, 7 bitop3:0x6c
	v_lshl_add_u32 v162, v3, 3, v5
	v_add_u32_e32 v3, 0x400, v2
	v_mul_hi_i32 v4, v3, s11
	v_lshrrev_b32_e32 v5, 31, v4
	v_ashrrev_i32_e32 v4, 2, v4
	v_add_u32_e32 v4, v4, v5
	s_ashr_i32 s14, s68, 4
	v_mul_lo_u32 v5, v4, 24
	s_and_b32 s15, s14, 0x1ffff0
	s_lshr_b32 s14, s14, 1
	v_sub_u32_e32 v3, v3, v5
	v_mul_lo_u32 v5, v4, s18
	v_lshrrev_b32_e32 v4, 1, v4
	s_and_b32 s14, s14, 4
	v_bitop3_b32 v3, v4, v3, 7 bitop3:0x6c
	s_or_b32 s14, s15, s14
	v_lshl_add_u32 v170, v3, 3, v5
	v_or_b32_e32 v3, s14, v169
	s_add_i32 s14, s68, 0x200
	s_ashr_i32 s14, s14, 4
	s_and_b32 s15, s14, 0x1ffff0
	s_lshr_b32 s14, s14, 1
	s_and_b32 s14, s14, 4
	v_and_or_b32 v2, v2, s10, v165
	s_or_b32 s14, s15, s14
	v_lshl_or_b32 v172, v3, 11, v2
	v_or_b32_e32 v3, s14, v169
	s_lshl_b32 s14, s20, 10
	s_add_i32 s69, s14, 0
	v_ashrrev_i32_e32 v161, 31, v160
	v_lshl_or_b32 v174, v3, 11, v2
	s_add_i32 m0, s69, 0x8000
	v_lshl_add_u64 v[2:3], v[160:161], 1, s[12:13]
	v_ashrrev_i32_e32 v163, 31, v162
	global_load_lds_dwordx4 v[2:3], off
	v_lshl_add_u64 v[2:3], v[162:163], 1, s[12:13]
	s_add_i32 m0, s69, 0xa000
	v_ashrrev_i32_e32 v171, 31, v170
	global_load_lds_dwordx4 v[2:3], off
	v_lshl_add_u64 v[2:3], v[170:171], 1, s[12:13]
	s_add_i32 m0, s69, 0xc000
	v_ashrrev_i32_e32 v173, 31, v172
	global_load_lds_dwordx4 v[2:3], off
	v_lshl_add_u64 v[2:3], v[172:173], 1, s[0:1]
	v_lshl_add_u64 v[2:3], v[2:3], 0, s[6:7]
	s_mov_b32 m0, s69
	v_ashrrev_i32_e32 v175, 31, v174
	global_load_lds_dwordx4 v[2:3], off
	v_lshl_add_u64 v[2:3], v[174:175], 1, s[0:1]
	v_lshl_add_u64 v[2:3], v[2:3], 0, s[6:7]
	s_add_i32 m0, s69, 0x2000
	v_mov_b32_e32 v151, 0
	global_load_lds_dwordx4 v[2:3], off
	s_waitcnt vmcnt(0)
	s_add_i32 s0, s4, 1
	s_mov_b32 s4, 0
	s_mov_b64 s[14:15], 0x80
	v_mov_b32_e32 v2, 0
	v_mov_b32_e32 v3, v151
	v_mov_b32_e32 v4, v151
	v_mov_b32_e32 v5, v151
	v_mov_b32_e32 v6, v151
	v_mov_b32_e32 v7, v151
	v_mov_b32_e32 v8, v151
	v_mov_b32_e32 v9, v151
	v_mov_b32_e32 v10, v151
	v_mov_b32_e32 v11, v151
	v_mov_b32_e32 v12, v151
	v_mov_b32_e32 v13, v151
	v_mov_b32_e32 v14, v151
	v_mov_b32_e32 v15, v151
	v_mov_b32_e32 v16, v151
	v_mov_b32_e32 v17, v151
	v_mov_b32_e32 v18, 0
	v_mov_b32_e32 v19, v151
	v_mov_b32_e32 v20, v151
	v_mov_b32_e32 v21, v151
	v_mov_b32_e32 v22, v151
	v_mov_b32_e32 v23, v151
	v_mov_b32_e32 v24, v151
	v_mov_b32_e32 v25, v151
	v_mov_b32_e32 v26, v151
	v_mov_b32_e32 v27, v151
	v_mov_b32_e32 v28, v151
	v_mov_b32_e32 v29, v151
	v_mov_b32_e32 v30, v151
	v_mov_b32_e32 v31, v151
	v_mov_b32_e32 v32, v151
	v_mov_b32_e32 v33, v151
	v_mov_b32_e32 v34, 0
	v_mov_b32_e32 v35, v151
	v_mov_b32_e32 v36, v151
	v_mov_b32_e32 v37, v151
	v_mov_b32_e32 v38, v151
	v_mov_b32_e32 v39, v151
	v_mov_b32_e32 v40, v151
	v_mov_b32_e32 v41, v151
	v_mov_b32_e32 v42, v151
	v_mov_b32_e32 v43, v151
	v_mov_b32_e32 v44, v151
	v_mov_b32_e32 v45, v151
	v_mov_b32_e32 v46, v151
	v_mov_b32_e32 v47, v151
	v_mov_b32_e32 v48, v151
	v_mov_b32_e32 v49, v151
	v_mov_b32_e32 v50, 0
	v_mov_b32_e32 v51, v151
	v_mov_b32_e32 v52, v151
	v_mov_b32_e32 v53, v151
	v_mov_b32_e32 v54, v151
	v_mov_b32_e32 v55, v151
	v_mov_b32_e32 v56, v151
	v_mov_b32_e32 v57, v151
	v_mov_b32_e32 v58, v151
	v_mov_b32_e32 v59, v151
	v_mov_b32_e32 v60, v151
	v_mov_b32_e32 v61, v151
	v_mov_b32_e32 v62, v151
	v_mov_b32_e32 v63, v151
	v_mov_b32_e32 v64, v151
	v_mov_b32_e32 v65, v151
	s_waitcnt vmcnt(0) lgkmcnt(0)
	s_barrier
	s_mov_b32 s98, 0
	s_mov_b32 s99, 0x4000
	s_mov_b32 s101, 0x1a000
	s_mov_b32 s100, 0
	s_add_u32 s38, s12, 0x30000
	s_addc_u32 s39, s13, 0
	s_add_u32 s28, s24, 0x40000
	s_addc_u32 s29, s25, 0
	s_add_i32 s36, s69, 0x6000
	s_add_i32 s21, s69, 0x4000
	s_add_i32 m0, s36, 0x8000
	v_lshl_add_u64 v[66:67], v[160:161], 1, s[38:39]
	global_load_lds_dwordx4 v[66:67], off
	s_add_i32 m0, s36, 0xa000
	v_lshl_add_u64 v[68:69], v[162:163], 1, s[38:39]
	global_load_lds_dwordx4 v[68:69], off
	s_add_i32 m0, s36, 0xc000
	v_lshl_add_u64 v[66:67], v[170:171], 1, s[38:39]
	global_load_lds_dwordx4 v[66:67], off
	s_mov_b32 m0, s21
	v_lshl_add_u64 v[68:69], v[172:173], 1, s[28:29]
	global_load_lds_dwordx4 v[68:69], off
	s_add_i32 m0, s21, 0x2000
	v_lshl_add_u64 v[66:67], v[174:175], 1, s[28:29]
	global_load_lds_dwordx4 v[66:67], off
	.p2alignl 6, 3212836864

.LBB0_904:
	v_add_f32_e32 v1, v1, v116
	s_add_u32 s0, s18, 0x240000
	v_add_f32_e32 v1, 0, v1
	v_add_f32_e32 v66, v66, v67
	s_addc_u32 s1, s19, 0
	v_add_f32_e32 v1, v1, v66
	v_lshl_add_u64 v[66:67], v[72:73], 1, s[0:1]
	s_mov_b32 m0, s35
	v_exp_f32_e32 v175, v106
	global_load_lds_dwordx4 v[66:67], off
	v_lshl_add_u64 v[66:67], v[70:71], 1, s[0:1]
	s_mov_b32 m0, s86
	v_exp_f32_e32 v176, v107
	global_load_lds_dwordx4 v[66:67], off
	v_exp_f32_e32 v177, v108
	v_exp_f32_e32 v178, v109
	v_exp_f32_e32 v179, v110
	v_exp_f32_e32 v180, v111
	v_exp_f32_e32 v181, v112
	v_exp_f32_e32 v192, v113
	ds_read_b128 v[66:69], v188 offset:40960
	ds_read_b128 v[70:73], v188 offset:45056
	ds_read_b128 v[106:109], v189 offset:40960
	ds_read_b128 v[110:113], v189 offset:45056
	ds_read_b128 v[116:119], v190 offset:40960
	ds_read_b128 v[120:123], v190 offset:45056
	ds_read_b128 v[124:127], v191 offset:40960
	ds_read_b128 v[170:173], v191 offset:45056
	v_exp_f32_e32 v151, v98
	v_exp_f32_e32 v153, v99
	v_exp_f32_e32 v155, v100
	v_exp_f32_e32 v157, v101
	v_exp_f32_e32 v159, v102
	v_exp_f32_e32 v161, v103
	v_exp_f32_e32 v163, v104
	v_exp_f32_e32 v174, v105
	s_waitcnt lgkmcnt(0)
	v_mfma_f32_32x32x16_bf16 v[90:105], v[66:69], v[128:131], 0
	v_exp_f32_e32 v193, v74
	v_exp_f32_e32 v194, v75
	v_exp_f32_e32 v195, v76
	v_exp_f32_e32 v196, v77
	v_exp_f32_e32 v197, v78
	v_exp_f32_e32 v198, v79
	v_exp_f32_e32 v199, v80
	v_exp_f32_e32 v200, v81
	v_mfma_f32_32x32x16_bf16 v[66:81], v[70:73], v[128:131], 0
	v_mfma_f32_32x32x16_bf16 v[90:105], v[106:109], v[132:135], v[90:105]
	v_exp_f32_e32 v82, v82
	v_exp_f32_e32 v83, v83
	v_exp_f32_e32 v84, v84
	v_exp_f32_e32 v85, v85
	v_exp_f32_e32 v86, v86
	v_exp_f32_e32 v87, v87
	v_exp_f32_e32 v88, v88
	v_mfma_f32_32x32x16_bf16 v[66:81], v[110:113], v[132:135], v[66:81]
	v_exp_f32_e32 v89, v89
	v_add_f32_e32 v106, v151, v153
	v_add_f32_e32 v107, v193, v194
	v_mfma_f32_32x32x16_bf16 v[90:105], v[116:119], v[136:139], v[90:105]
	v_add_f32_e32 v106, v106, v155
	v_add_f32_e32 v107, v107, v195
	v_cvt_pk_bf16_f32 v108, v159, v161
	v_add_f32_e32 v106, v106, v157
	v_add_f32_e32 v107, v107, v196
	v_cvt_pk_bf16_f32 v109, v163, v174
	v_add_f32_e32 v106, v106, v159
	v_add_f32_e32 v107, v107, v197
	v_mfma_f32_32x32x16_bf16 v[66:81], v[120:123], v[136:139], v[66:81]
	v_add_f32_e32 v106, v106, v161
	v_add_f32_e32 v107, v107, v198
	s_nop 0
	v_add_f32_e32 v106, v106, v163
	v_add_f32_e32 v107, v107, v199
	s_nop 0
	v_add_f32_e32 v106, v106, v174
	v_add_f32_e32 v107, v107, v200
	s_nop 0
	v_add_f32_e32 v106, v106, v175
	v_add_f32_e32 v107, v107, v82
	s_nop 0
	v_add_f32_e32 v106, v106, v176
	v_add_f32_e32 v107, v107, v83
	s_nop 0
	v_add_f32_e32 v106, v106, v177
	v_add_f32_e32 v107, v107, v84
	s_nop 0
	v_add_f32_e32 v106, v106, v178
	v_add_f32_e32 v107, v107, v85
	s_nop 0
	v_add_f32_e32 v106, v106, v179
	v_add_f32_e32 v107, v107, v86
	s_nop 0
	v_add_f32_e32 v106, v106, v180
	v_add_f32_e32 v107, v107, v87
	s_nop 0
	v_add_f32_e32 v106, v106, v181
	v_add_f32_e32 v107, v107, v88
	s_nop 0
	v_add_f32_e32 v106, v106, v192
	v_add_f32_e32 v107, v107, v89
	s_nop 0
	v_add_f32_e32 v106, v106, v107
	v_mov_b32_e32 v107, v106
	s_nop 1
	v_permlane32_swap_b32_e32 v106, v107
	v_add_f32_e32 v106, v106, v107
	v_add_f32_e32 v149, v1, v106
	v_cvt_pk_bf16_f32 v106, v151, v153
	v_cvt_pk_bf16_f32 v107, v155, v157
	s_nop 0
	v_permlane32_swap_b32_e32 v106, v108
	v_permlane32_swap_b32_e32 v107, v109
	v_mfma_f32_32x32x16_bf16 v[90:105], v[124:127], v[140:143], v[90:105]
	v_cvt_pk_bf16_f32 v110, v175, v176
	v_cvt_pk_bf16_f32 v111, v177, v178
	v_cvt_pk_bf16_f32 v112, v179, v180
	v_cvt_pk_bf16_f32 v113, v181, v192
	v_cvt_pk_bf16_f32 v116, v193, v194
	v_cvt_pk_bf16_f32 v117, v195, v196
	v_cvt_pk_bf16_f32 v118, v197, v198
	v_mfma_f32_32x32x16_bf16 v[66:81], v[170:173], v[140:143], v[66:81]
	v_cvt_pk_bf16_f32 v119, v199, v200
	v_cvt_pk_bf16_f32 v120, v82, v83
	v_cvt_pk_bf16_f32 v121, v84, v85
	v_cvt_pk_bf16_f32 v122, v86, v87
	v_cvt_pk_bf16_f32 v123, v88, v89
	v_permlane32_swap_b32_e32 v110, v112
	v_permlane32_swap_b32_e32 v111, v113
	v_permlane32_swap_b32_e32 v116, v118
	v_permlane32_swap_b32_e32 v117, v119
	v_permlane32_swap_b32_e32 v120, v122
	v_permlane32_swap_b32_e32 v121, v123
	ds_read_b64_tr_b16 v[82:83], v184 offset:0
	ds_read_b64_tr_b16 v[84:85], v184 offset:0x800
	ds_read_b64_tr_b16 v[86:87], v184 offset:0x1000
	ds_read_b64_tr_b16 v[88:89], v184 offset:0x1800
	ds_read_b64_tr_b16 v[124:125], v184 offset:0x2000
	ds_read_b64_tr_b16 v[126:127], v184 offset:0x2800
	ds_read_b64_tr_b16 v[170:171], v184 offset:0x3000
	ds_read_b64_tr_b16 v[172:173], v184 offset:0x3800
	ds_read_b64_tr_b16 v[174:175], v184 offset:0x200
	ds_read_b64_tr_b16 v[176:177], v184 offset:0xa00
	ds_read_b64_tr_b16 v[178:179], v184 offset:0x1200
	ds_read_b64_tr_b16 v[180:181], v184 offset:0x1a00
	ds_read_b64_tr_b16 v[192:193], v184 offset:0x2200
	ds_read_b64_tr_b16 v[194:195], v184 offset:0x2a00
	ds_read_b64_tr_b16 v[196:197], v184 offset:0x3200
	ds_read_b64_tr_b16 v[198:199], v184 offset:0x3a00
	s_waitcnt lgkmcnt(8)
	s_nop 0
	v_mfma_f32_32x32x16_bf16 v[2:17], v[106:109], v[82:85], v[2:17]
	v_exp_f32_e32 v1, v91
	v_exp_f32_e32 v82, v92
	v_exp_f32_e32 v83, v93
	v_mfma_f32_32x32x16_bf16 v[2:17], v[110:113], v[86:89], v[2:17]
	v_exp_f32_e32 v88, v90
	v_mfma_f32_32x32x16_bf16 v[2:17], v[116:119], v[124:127], v[2:17]
	v_mfma_f32_32x32x16_bf16 v[2:17], v[120:123], v[170:173], v[2:17]
	ds_read_b64_tr_b16 v[90:91], v184 offset:0x400
	ds_read_b64_tr_b16 v[92:93], v184 offset:0xc00
	ds_read_b64_tr_b16 v[124:125], v184 offset:0x1400
	ds_read_b64_tr_b16 v[126:127], v184 offset:0x1c00
	ds_read_b64_tr_b16 v[170:171], v184 offset:0x2400
	ds_read_b64_tr_b16 v[172:173], v184 offset:0x2c00
	ds_read_b64_tr_b16 v[200:201], v184 offset:0x3400
	ds_read_b64_tr_b16 v[202:203], v184 offset:0x3c00
	s_waitcnt lgkmcnt(8)
	v_mfma_f32_32x32x16_bf16 v[18:33], v[106:109], v[174:177], v[18:33]
	v_exp_f32_e32 v84, v94
	v_exp_f32_e32 v85, v95
	v_exp_f32_e32 v86, v96
	v_exp_f32_e32 v87, v97
	v_mfma_f32_32x32x16_bf16 v[18:33], v[110:113], v[178:181], v[18:33]
	v_mfma_f32_32x32x16_bf16 v[18:33], v[116:119], v[192:195], v[18:33]
	v_mfma_f32_32x32x16_bf16 v[18:33], v[120:123], v[196:199], v[18:33]
	ds_read_b64_tr_b16 v[94:95], v184 offset:0x600
	ds_read_b64_tr_b16 v[96:97], v184 offset:0xe00
	ds_read_b64_tr_b16 v[174:175], v184 offset:0x1600
	ds_read_b64_tr_b16 v[176:177], v184 offset:0x1e00
	ds_read_b64_tr_b16 v[178:179], v184 offset:0x2600
	ds_read_b64_tr_b16 v[180:181], v184 offset:0x2e00
	ds_read_b64_tr_b16 v[192:193], v184 offset:0x3600
	ds_read_b64_tr_b16 v[194:195], v184 offset:0x3e00
	s_waitcnt lgkmcnt(8)
	v_mfma_f32_32x32x16_bf16 v[34:49], v[106:109], v[90:93], v[34:49]
	v_exp_f32_e32 v90, v98
	v_exp_f32_e32 v89, v99
	v_exp_f32_e32 v92, v100
	v_exp_f32_e32 v91, v101
	v_mfma_f32_32x32x16_bf16 v[34:49], v[110:113], v[124:127], v[34:49]
	v_mfma_f32_32x32x16_bf16 v[34:49], v[116:119], v[170:173], v[34:49]
	v_mfma_f32_32x32x16_bf16 v[34:49], v[120:123], v[200:203], v[34:49]
	s_waitcnt lgkmcnt(0)
	v_mfma_f32_32x32x16_bf16 v[50:65], v[106:109], v[94:97], v[50:65]
	v_exp_f32_e32 v94, v102
	v_exp_f32_e32 v93, v103
	v_exp_f32_e32 v95, v104
	v_exp_f32_e32 v151, v105
	v_mfma_f32_32x32x16_bf16 v[50:65], v[110:113], v[174:177], v[50:65]
	v_mfma_f32_32x32x16_bf16 v[50:65], v[116:119], v[178:181], v[50:65]
	v_mfma_f32_32x32x16_bf16 v[50:65], v[120:123], v[192:195], v[50:65]
	s_waitcnt vmcnt(0)
	s_and_b64 vcc, exec, s[4:5]
	s_waitcnt vmcnt(0)
	s_barrier
	s_cbranch_vccnz .LBB0_911
	v_readlane_b32 s36, v243, 63
	v_readlane_b32 s50, v242, 13
	v_readlane_b32 s51, v242, 14
	s_add_u32 s4, s50, s88
	v_mov_b32_e32 v96, s25
	v_mov_b32_e32 v97, v145
	s_addc_u32 s5, s51, s87
	s_add_i32 s92, s92, s91
	v_lshl_add_u64 v[170:171], v[114:115], 1, v[96:97]
	v_add_u32_e32 v96, s92, v182
	v_add_u32_e32 v97, s10, v166
	v_mul_lo_u32 v96, v96, s22
	v_and_b32_e32 v98, 0x60, v97
	v_or3_b32 v96, v169, v96, v98
	v_ashrrev_i32_e32 v97, 31, v96
	s_add_i32 s90, s90, s89
	v_lshlrev_b64 v[172:173], 1, v[96:97]
	v_add_u32_e32 v96, s90, v182
	v_mul_lo_u32 v96, v96, s22
	v_or3_b32 v96, v169, v96, v98
	v_ashrrev_i32_e32 v97, 31, v96
	v_lshlrev_b64 v[174:175], 1, v[96:97]
	v_or_b32_e32 v172, s24, v172
	v_or_b32_e32 v174, s24, v174
	s_mov_b32 s16, 6
	v_readlane_b32 s37, v242, 0
	v_readlane_b32 s38, v242, 1
	v_readlane_b32 s39, v242, 2
	v_readlane_b32 s40, v242, 3
	v_readlane_b32 s41, v242, 4
	v_readlane_b32 s42, v242, 5
	v_readlane_b32 s43, v242, 6
	v_readlane_b32 s44, v242, 7
	v_readlane_b32 s45, v242, 8
	v_readlane_b32 s46, v242, 9
	v_readlane_b32 s47, v242, 10
	v_readlane_b32 s48, v242, 11
	v_readlane_b32 s49, v242, 12
	v_exp_f32_e32 v66, v66
	v_exp_f32_e32 v67, v67
	v_exp_f32_e32 v68, v68
	v_exp_f32_e32 v69, v69
	v_exp_f32_e32 v70, v70
	v_exp_f32_e32 v71, v71
	v_exp_f32_e32 v72, v72
	v_exp_f32_e32 v73, v73
	v_exp_f32_e32 v74, v74
	v_exp_f32_e32 v75, v75
	v_exp_f32_e32 v76, v76
	v_exp_f32_e32 v77, v77
	v_exp_f32_e32 v78, v78
	v_exp_f32_e32 v79, v79
	v_exp_f32_e32 v80, v80
	v_exp_f32_e32 v81, v81
	v_add_f32_e32 v96, v88, v1
	v_add_f32_e32 v97, v66, v67
	v_add_f32_e32 v96, v96, v82
	v_add_f32_e32 v97, v97, v68
	v_add_f32_e32 v96, v96, v83
	v_add_f32_e32 v97, v97, v69
	v_add_f32_e32 v96, v96, v84
	v_add_f32_e32 v97, v97, v70
	v_add_f32_e32 v96, v96, v85
	v_add_f32_e32 v97, v97, v71
	v_add_f32_e32 v96, v96, v86
	v_add_f32_e32 v97, v97, v72
	v_add_f32_e32 v96, v96, v87
	v_add_f32_e32 v97, v97, v73
	v_add_f32_e32 v96, v96, v90
	v_add_f32_e32 v97, v97, v74
	v_add_f32_e32 v96, v96, v89
	v_add_f32_e32 v97, v97, v75
	v_add_f32_e32 v96, v96, v92
	v_add_f32_e32 v97, v97, v76
	v_add_f32_e32 v96, v96, v91
	v_add_f32_e32 v97, v97, v77
	v_add_f32_e32 v96, v96, v94
	v_add_f32_e32 v97, v97, v78
	v_add_f32_e32 v96, v96, v93
	v_add_f32_e32 v97, v97, v79
	v_add_f32_e32 v96, v96, v95
	v_add_f32_e32 v97, v97, v80
	v_add_f32_e32 v96, v96, v151
	v_add_f32_e32 v97, v97, v81
	v_add_f32_e32 v96, v96, v97
	v_mov_b32_e32 v98, v96
	v_cvt_pk_bf16_f32 v222, v88, v1
	v_cvt_pk_bf16_f32 v223, v82, v83
	v_cvt_pk_bf16_f32 v224, v84, v85
	v_cvt_pk_bf16_f32 v225, v86, v87
	v_cvt_pk_bf16_f32 v226, v90, v89
	v_cvt_pk_bf16_f32 v227, v92, v91
	v_cvt_pk_bf16_f32 v228, v94, v93
	v_cvt_pk_bf16_f32 v229, v95, v151
	v_cvt_pk_bf16_f32 v230, v66, v67
	v_cvt_pk_bf16_f32 v231, v68, v69
	v_cvt_pk_bf16_f32 v232, v70, v71
	v_cvt_pk_bf16_f32 v233, v72, v73
	v_cvt_pk_bf16_f32 v234, v74, v75
	v_cvt_pk_bf16_f32 v235, v76, v77
	v_cvt_pk_bf16_f32 v236, v78, v79
	v_cvt_pk_bf16_f32 v237, v80, v81
	v_permlane32_swap_b32_e32 v96, v98
	v_add_f32_e32 v96, v96, v98
	v_add_f32_e32 v149, v149, v96
	v_permlane32_swap_b32_e32 v222, v224
	v_permlane32_swap_b32_e32 v223, v225
	v_permlane32_swap_b32_e32 v226, v228
	v_permlane32_swap_b32_e32 v227, v229
	v_permlane32_swap_b32_e32 v230, v232
	v_permlane32_swap_b32_e32 v231, v233
	v_permlane32_swap_b32_e32 v234, v236
	v_permlane32_swap_b32_e32 v235, v237
	s_branch .LBB0_907
	.p2alignl 6, 3212836864
